# PEER token tail: second half's gain/scale/shift loads issued together with the first half's (before the first h store) with recounted waits (on top of v49)
# speedup vs baseline: 1.0025x; 1.0025x over previous
.LBB0_900:
	s_waitcnt vmcnt(34)
	v_pk_fma_f32 v[16:17], v[16:17], v[208:209], v[0:1]
	v_add_u32_e32 v0, 5, v144
	v_mad_u64_u32 v[44:45], s[10:11], v0, s27, v[108:109]
	v_pk_fma_f32 v[12:13], v[28:29], v[200:201], v[12:13]
	v_pk_fma_f32 v[14:15], v[30:31], v[218:219], v[14:15]
	s_waitcnt vmcnt(32)
	v_pk_fma_f32 v[24:25], v[24:25], v[216:217], v[8:9]
	v_pk_fma_f32 v[26:27], v[26:27], v[214:215], v[10:11]
	v_pk_fma_f32 v[8:9], v[20:21], v[212:213], v[4:5]
	v_pk_fma_f32 v[10:11], v[22:23], v[210:211], v[6:7]
	v_pk_fma_f32 v[18:19], v[18:19], v[206:207], v[2:3]
	v_add_co_u32_e32 v46, vcc, s57, v44
	global_store_dwordx4 v[162:163], v[12:15], off
	global_store_dwordx4 v[162:163], v[24:27], off offset:16
	global_store_dwordx4 v[162:163], v[8:11], off offset:32
	global_store_dwordx4 v[162:163], v[16:19], off offset:48
	v_addc_co_u32_e32 v47, vcc, 0, v45, vcc
	global_load_dwordx4 v[0:3], v[106:107], off offset:16
	global_load_dwordx4 v[4:7], v[106:107], off
	global_load_dwordx4 v[20:23], v[46:47], off
	v_lshl_add_u64 v[28:29], v[44:45], 0, s[16:17]
	global_load_dwordx4 v[28:31], v[28:29], off offset:16
	s_nop 0
	global_load_dwordx4 v[32:35], v[44:45], off offset:16
	global_load_dwordx4 v[36:39], v[44:45], off
	v_mov_b32_e32 v60, v0
	v_mov_b32_e32 v61, v1
	global_load_dwordx4 v[202:205], v[106:107], off offset:32
	global_load_dwordx4 v[196:199], v[46:47], off offset:32
	global_load_dwordx4 v[192:195], v[106:107], off offset:48
	v_lshl_add_u64 v[60:61], v[44:45], 0, s[22:23]
	global_load_dwordx4 v[188:191], v[60:61], off offset:16
	global_load_dwordx4 v[184:187], v[44:45], off offset:32
	global_load_dwordx4 v[180:183], v[44:45], off offset:48
	v_pk_mul_f32 v[40:41], v[12:13], v[12:13]
	v_pk_mul_f32 v[42:43], v[14:15], v[14:15]
	v_add_f32_e32 v40, v40, v41
	v_add_f32_e32 v40, v40, v42
	v_pk_mul_f32 v[48:49], v[24:25], v[24:25]
	v_add_f32_e32 v40, v43, v40
	v_add_f32_e32 v40, v48, v40
	v_pk_mul_f32 v[50:51], v[26:27], v[26:27]
	v_add_f32_e32 v40, v49, v40
	v_add_f32_e32 v40, v50, v40
	v_pk_mul_f32 v[52:53], v[8:9], v[8:9]
	v_add_f32_e32 v40, v51, v40
	v_add_f32_e32 v40, v52, v40
	v_pk_mul_f32 v[54:55], v[10:11], v[10:11]
	v_add_f32_e32 v40, v53, v40
	v_add_f32_e32 v40, v54, v40
	v_pk_mul_f32 v[56:57], v[16:17], v[16:17]
	v_add_f32_e32 v40, v55, v40
	v_add_f32_e32 v40, v56, v40
	v_pk_mul_f32 v[58:59], v[18:19], v[18:19]
	v_add_f32_e32 v40, v57, v40
	v_add_f32_e32 v40, v58, v40
	v_add_f32_e32 v40, v59, v40
	v_accvgpr_read_b32 v41, a71
	ds_bpermute_b32 v41, v41, v40
	v_mov_b32_e32 v42, 0x358637bd
	v_mov_b32_e32 v102, v118
	v_mov_b32_e32 v116, v120
	s_waitcnt vmcnt(19)
	v_accvgpr_read_b32 v142, a68
	s_waitcnt lgkmcnt(0)
	v_add_f32_e32 v40, v40, v41
	v_accvgpr_read_b32 v41, a74
	ds_bpermute_b32 v41, v41, v40
	s_waitcnt vmcnt(18)
	v_accvgpr_read_b32 v143, a69
	s_waitcnt lgkmcnt(0)
	v_add_f32_e32 v40, v40, v41
	v_accvgpr_read_b32 v41, a75
	ds_bpermute_b32 v41, v41, v40
	s_waitcnt lgkmcnt(0)
	v_add_f32_e32 v40, v40, v41
	ds_bpermute_b32 v41, v135, v40
	s_waitcnt lgkmcnt(0)
	v_add_f32_e32 v40, v40, v41
	ds_bpermute_b32 v41, v129, v40
	s_waitcnt lgkmcnt(0)
	v_add_f32_e32 v40, v40, v41
	ds_bpermute_b32 v41, v131, v40
	s_waitcnt lgkmcnt(0)
	v_add_f32_e32 v40, v40, v41
	v_fmamk_f32 v40, v40, 0x3a800000, v42
	v_mul_f32_e32 v41, 0x4b800000, v40
	v_cmp_gt_f32_e32 vcc, s56, v40
	s_nop 1
	v_cndmask_b32_e32 v40, v40, v41, vcc
	v_rsq_f32_e32 v42, v40
	v_lshl_add_u64 v[40:41], v[122:123], 1, v[104:105]
	v_mul_f32_e32 v43, 0x45800000, v42
	v_cndmask_b32_e32 v42, v42, v43, vcc
	v_pk_mul_f32 v[12:13], v[12:13], v[42:43] op_sel_hi:[1,0]
	v_pk_mul_f32 v[14:15], v[14:15], v[42:43] op_sel_hi:[1,0]
	v_pk_mul_f32 v[24:25], v[24:25], v[42:43] op_sel_hi:[1,0]
	v_pk_mul_f32 v[26:27], v[26:27], v[42:43] op_sel_hi:[1,0]
	s_waitcnt vmcnt(10)
	v_pk_mul_f32 v[4:5], v[4:5], v[12:13]
	v_pk_mul_f32 v[6:7], v[6:7], v[14:15]
	v_pk_mul_f32 v[0:1], v[24:25], v[0:1]
	v_pk_mul_f32 v[2:3], v[26:27], v[2:3]
	s_waitcnt vmcnt(9)
	v_pk_add_f32 v[12:13], v[20:21], 1.0 op_sel_hi:[1,0]
	v_pk_add_f32 v[14:15], v[22:23], 1.0 op_sel_hi:[1,0]
	s_waitcnt vmcnt(8)
	v_pk_add_f32 v[20:21], v[28:29], 1.0 op_sel_hi:[1,0]
	v_pk_add_f32 v[22:23], v[30:31], 1.0 op_sel_hi:[1,0]
	s_waitcnt vmcnt(6)
	v_pk_fma_f32 v[4:5], v[12:13], v[4:5], v[36:37]
	v_pk_fma_f32 v[6:7], v[6:7], v[14:15], v[38:39]
	v_pk_fma_f32 v[12:13], v[0:1], v[20:21], v[32:33]
	v_pk_fma_f32 v[14:15], v[2:3], v[22:23], v[34:35]
	v_cvt_pk_bf16_f32 v0, v4, v5
	v_cvt_pk_bf16_f32 v1, v6, v7
	v_cvt_pk_bf16_f32 v2, v12, v13
	v_cvt_pk_bf16_f32 v3, v14, v15
	global_store_dwordx4 v[40:41], v[0:3], off
	s_waitcnt vmcnt(6)
	s_nop 1
	v_mov_b64_e32 v[12:13], v[202:203]
	v_mov_b64_e32 v[14:15], v[204:205]
	s_waitcnt vmcnt(5)
	s_nop 1
	v_mov_b64_e32 v[20:21], v[196:197]
	v_mov_b64_e32 v[22:23], v[198:199]
	s_waitcnt vmcnt(4)
	s_nop 1
	v_mov_b64_e32 v[24:25], v[192:193]
	v_mov_b64_e32 v[26:27], v[194:195]
	v_lshl_add_u64 v[0:1], v[44:45], 0, s[22:23]
	s_waitcnt vmcnt(3)
	s_nop 1
	v_mov_b64_e32 v[28:29], v[188:189]
	v_mov_b64_e32 v[30:31], v[190:191]
	s_waitcnt vmcnt(2)
	s_nop 1
	v_mov_b64_e32 v[32:33], v[184:185]
	v_mov_b64_e32 v[34:35], v[186:187]
	s_waitcnt vmcnt(1)
	s_nop 1
	v_mov_b64_e32 v[36:37], v[180:181]
	v_mov_b64_e32 v[38:39], v[182:183]
	v_pk_mul_f32 v[8:9], v[8:9], v[42:43] op_sel_hi:[1,0]
	v_pk_mul_f32 v[10:11], v[10:11], v[42:43] op_sel_hi:[1,0]
	v_pk_mul_f32 v[16:17], v[16:17], v[42:43] op_sel_hi:[1,0]
	v_pk_mul_f32 v[18:19], v[18:19], v[42:43] op_sel_hi:[1,0]
	v_cmp_lt_i32_e32 vcc, s31, v128
	v_accvgpr_read_b32 v4, a36
	v_accvgpr_read_b32 v0, a32
	v_accvgpr_read_b32 v5, a37
	v_accvgpr_read_b32 v6, a38
	v_accvgpr_read_b32 v7, a39
	v_accvgpr_read_b32 v1, a33
	v_accvgpr_read_b32 v2, a34
	v_accvgpr_read_b32 v3, a35
	s_or_b64 s[18:19], vcc, s[18:19]
	v_pk_mul_f32 v[8:9], v[8:9], v[12:13]
	v_pk_add_f32 v[12:13], v[20:21], 1.0 op_sel_hi:[1,0]
	v_pk_mul_f32 v[10:11], v[10:11], v[14:15]
	v_pk_add_f32 v[14:15], v[22:23], 1.0 op_sel_hi:[1,0]
	v_pk_mul_f32 v[16:17], v[16:17], v[24:25]
	v_pk_add_f32 v[20:21], v[28:29], 1.0 op_sel_hi:[1,0]
	v_pk_mul_f32 v[18:19], v[18:19], v[26:27]
	v_pk_add_f32 v[22:23], v[30:31], 1.0 op_sel_hi:[1,0]
	v_pk_fma_f32 v[8:9], v[8:9], v[12:13], v[32:33]
	v_pk_fma_f32 v[10:11], v[10:11], v[14:15], v[34:35]
	v_pk_fma_f32 v[12:13], v[16:17], v[20:21], v[36:37]
	v_pk_fma_f32 v[14:15], v[18:19], v[22:23], v[38:39]
	v_cvt_pk_bf16_f32 v8, v8, v9
	v_cvt_pk_bf16_f32 v9, v10, v11
	v_cvt_pk_bf16_f32 v10, v12, v13
	v_cvt_pk_bf16_f32 v11, v14, v15
	global_store_dwordx4 v[40:41], v[8:11], off offset:16
	s_andn2_b64 exec, exec, s[18:19]
	s_cbranch_execz .LBB0_922

.LBB0_1385:
	s_waitcnt vmcnt(34)
	v_pk_fma_f32 v[16:17], v[16:17], v[208:209], v[0:1]
	v_add_u32_e32 v0, 10, v144
	v_mad_u64_u32 v[44:45], s[12:13], v0, s27, v[108:109]
	v_pk_fma_f32 v[12:13], v[28:29], v[200:201], v[12:13]
	v_pk_fma_f32 v[14:15], v[30:31], v[218:219], v[14:15]
	s_waitcnt vmcnt(32)
	v_pk_fma_f32 v[24:25], v[24:25], v[216:217], v[8:9]
	v_pk_fma_f32 v[26:27], v[26:27], v[214:215], v[10:11]
	v_pk_fma_f32 v[8:9], v[20:21], v[212:213], v[4:5]
	v_pk_fma_f32 v[10:11], v[22:23], v[210:211], v[6:7]
	v_pk_fma_f32 v[18:19], v[18:19], v[206:207], v[2:3]
	v_add_co_u32_e32 v46, vcc, s57, v44
	global_store_dwordx4 v[162:163], v[12:15], off
	global_store_dwordx4 v[162:163], v[24:27], off offset:16
	global_store_dwordx4 v[162:163], v[8:11], off offset:32
	global_store_dwordx4 v[162:163], v[16:19], off offset:48
	v_addc_co_u32_e32 v47, vcc, 0, v45, vcc
	global_load_dwordx4 v[0:3], v[106:107], off offset:16
	global_load_dwordx4 v[4:7], v[106:107], off
	global_load_dwordx4 v[20:23], v[46:47], off
	v_lshl_add_u64 v[28:29], v[44:45], 0, s[20:21]
	global_load_dwordx4 v[28:31], v[28:29], off offset:16
	s_nop 0
	global_load_dwordx4 v[32:35], v[44:45], off offset:16
	global_load_dwordx4 v[36:39], v[44:45], off
	v_mov_b32_e32 v60, v0
	v_mov_b32_e32 v61, v1
	global_load_dwordx4 v[202:205], v[106:107], off offset:32
	global_load_dwordx4 v[196:199], v[46:47], off offset:32
	global_load_dwordx4 v[192:195], v[106:107], off offset:48
	v_lshl_add_u64 v[60:61], v[44:45], 0, s[22:23]
	global_load_dwordx4 v[188:191], v[60:61], off offset:16
	global_load_dwordx4 v[184:187], v[44:45], off offset:32
	global_load_dwordx4 v[180:183], v[44:45], off offset:48
	v_pk_mul_f32 v[40:41], v[12:13], v[12:13]
	v_pk_mul_f32 v[42:43], v[14:15], v[14:15]
	v_add_f32_e32 v40, v40, v41
	v_add_f32_e32 v40, v40, v42
	v_pk_mul_f32 v[48:49], v[24:25], v[24:25]
	v_add_f32_e32 v40, v43, v40
	v_add_f32_e32 v40, v48, v40
	v_pk_mul_f32 v[50:51], v[26:27], v[26:27]
	v_add_f32_e32 v40, v49, v40
	v_add_f32_e32 v40, v50, v40
	v_pk_mul_f32 v[52:53], v[8:9], v[8:9]
	v_add_f32_e32 v40, v51, v40
	v_add_f32_e32 v40, v52, v40
	v_pk_mul_f32 v[54:55], v[10:11], v[10:11]
	v_add_f32_e32 v40, v53, v40
	v_add_f32_e32 v40, v54, v40
	v_pk_mul_f32 v[56:57], v[16:17], v[16:17]
	v_add_f32_e32 v40, v55, v40
	v_add_f32_e32 v40, v56, v40
	v_pk_mul_f32 v[58:59], v[18:19], v[18:19]
	v_add_f32_e32 v40, v57, v40
	v_add_f32_e32 v40, v58, v40
	v_add_f32_e32 v40, v59, v40
	v_accvgpr_read_b32 v41, a71
	ds_bpermute_b32 v41, v41, v40
	v_mov_b32_e32 v42, 0x358637bd
	v_mov_b32_e32 v104, v118
	v_mov_b32_e32 v116, v120
	s_waitcnt vmcnt(19)
	v_accvgpr_read_b32 v142, a68
	s_waitcnt lgkmcnt(0)
	v_add_f32_e32 v40, v40, v41
	v_accvgpr_read_b32 v41, a74
	ds_bpermute_b32 v41, v41, v40
	s_waitcnt vmcnt(18)
	v_accvgpr_read_b32 v143, a69
	s_waitcnt lgkmcnt(0)
	v_add_f32_e32 v40, v40, v41
	v_accvgpr_read_b32 v41, a75
	ds_bpermute_b32 v41, v41, v40
	s_waitcnt lgkmcnt(0)
	v_add_f32_e32 v40, v40, v41
	ds_bpermute_b32 v41, v135, v40
	s_waitcnt lgkmcnt(0)
	v_add_f32_e32 v40, v40, v41
	ds_bpermute_b32 v41, v129, v40
	s_waitcnt lgkmcnt(0)
	v_add_f32_e32 v40, v40, v41
	ds_bpermute_b32 v41, v131, v40
	s_waitcnt lgkmcnt(0)
	v_add_f32_e32 v40, v40, v41
	v_fmamk_f32 v40, v40, 0x3a800000, v42
	v_mul_f32_e32 v41, 0x4b800000, v40
	v_cmp_gt_f32_e32 vcc, s56, v40
	s_nop 1
	v_cndmask_b32_e32 v40, v40, v41, vcc
	v_rsq_f32_e32 v42, v40
	v_lshl_add_u64 v[40:41], v[122:123], 1, v[102:103]
	v_mul_f32_e32 v43, 0x45800000, v42
	v_cndmask_b32_e32 v42, v42, v43, vcc
	v_pk_mul_f32 v[12:13], v[12:13], v[42:43] op_sel_hi:[1,0]
	v_pk_mul_f32 v[14:15], v[14:15], v[42:43] op_sel_hi:[1,0]
	v_pk_mul_f32 v[24:25], v[24:25], v[42:43] op_sel_hi:[1,0]
	v_pk_mul_f32 v[26:27], v[26:27], v[42:43] op_sel_hi:[1,0]
	s_waitcnt vmcnt(10)
	v_pk_mul_f32 v[4:5], v[4:5], v[12:13]
	v_pk_mul_f32 v[6:7], v[6:7], v[14:15]
	v_pk_mul_f32 v[0:1], v[24:25], v[0:1]
	v_pk_mul_f32 v[2:3], v[26:27], v[2:3]
	s_waitcnt vmcnt(9)
	v_pk_add_f32 v[12:13], v[20:21], 1.0 op_sel_hi:[1,0]
	v_pk_add_f32 v[14:15], v[22:23], 1.0 op_sel_hi:[1,0]
	s_waitcnt vmcnt(8)
	v_pk_add_f32 v[20:21], v[28:29], 1.0 op_sel_hi:[1,0]
	v_pk_add_f32 v[22:23], v[30:31], 1.0 op_sel_hi:[1,0]
	s_waitcnt vmcnt(6)
	v_pk_fma_f32 v[4:5], v[12:13], v[4:5], v[36:37]
	v_pk_fma_f32 v[6:7], v[6:7], v[14:15], v[38:39]
	v_pk_fma_f32 v[12:13], v[0:1], v[20:21], v[32:33]
	v_pk_fma_f32 v[14:15], v[2:3], v[22:23], v[34:35]
	v_cvt_pk_bf16_f32 v0, v4, v5
	v_cvt_pk_bf16_f32 v1, v6, v7
	v_cvt_pk_bf16_f32 v2, v12, v13
	v_cvt_pk_bf16_f32 v3, v14, v15
	global_store_dwordx4 v[40:41], v[0:3], off
	s_waitcnt vmcnt(6)
	s_nop 1
	v_mov_b64_e32 v[12:13], v[202:203]
	v_mov_b64_e32 v[14:15], v[204:205]
	s_waitcnt vmcnt(5)
	s_nop 1
	v_mov_b64_e32 v[20:21], v[196:197]
	v_mov_b64_e32 v[22:23], v[198:199]
	s_waitcnt vmcnt(4)
	s_nop 1
	v_mov_b64_e32 v[24:25], v[192:193]
	v_mov_b64_e32 v[26:27], v[194:195]
	v_lshl_add_u64 v[0:1], v[44:45], 0, s[22:23]
	s_waitcnt vmcnt(3)
	s_nop 1
	v_mov_b64_e32 v[28:29], v[188:189]
	v_mov_b64_e32 v[30:31], v[190:191]
	s_waitcnt vmcnt(2)
	s_nop 1
	v_mov_b64_e32 v[32:33], v[184:185]
	v_mov_b64_e32 v[34:35], v[186:187]
	s_waitcnt vmcnt(1)
	s_nop 1
	v_mov_b64_e32 v[36:37], v[180:181]
	v_mov_b64_e32 v[38:39], v[182:183]
	v_pk_mul_f32 v[8:9], v[8:9], v[42:43] op_sel_hi:[1,0]
	v_pk_mul_f32 v[10:11], v[10:11], v[42:43] op_sel_hi:[1,0]
	v_pk_mul_f32 v[16:17], v[16:17], v[42:43] op_sel_hi:[1,0]
	v_pk_mul_f32 v[18:19], v[18:19], v[42:43] op_sel_hi:[1,0]
	v_cmp_lt_i32_e32 vcc, s31, v128
	v_accvgpr_read_b32 v4, a36
	v_accvgpr_read_b32 v0, a32
	v_accvgpr_read_b32 v5, a37
	v_accvgpr_read_b32 v6, a38
	v_accvgpr_read_b32 v7, a39
	v_accvgpr_read_b32 v1, a33
	v_accvgpr_read_b32 v2, a34
	v_accvgpr_read_b32 v3, a35
	s_or_b64 s[18:19], vcc, s[18:19]
	v_pk_mul_f32 v[8:9], v[8:9], v[12:13]
	v_pk_add_f32 v[12:13], v[20:21], 1.0 op_sel_hi:[1,0]
	v_pk_mul_f32 v[10:11], v[10:11], v[14:15]
	v_pk_add_f32 v[14:15], v[22:23], 1.0 op_sel_hi:[1,0]
	v_pk_mul_f32 v[16:17], v[16:17], v[24:25]
	v_pk_add_f32 v[20:21], v[28:29], 1.0 op_sel_hi:[1,0]
	v_pk_mul_f32 v[18:19], v[18:19], v[26:27]
	v_pk_add_f32 v[22:23], v[30:31], 1.0 op_sel_hi:[1,0]
	v_pk_fma_f32 v[8:9], v[8:9], v[12:13], v[32:33]
	v_pk_fma_f32 v[10:11], v[10:11], v[14:15], v[34:35]
	v_pk_fma_f32 v[12:13], v[16:17], v[20:21], v[36:37]
	v_pk_fma_f32 v[14:15], v[18:19], v[22:23], v[38:39]
	v_cvt_pk_bf16_f32 v8, v8, v9
	v_cvt_pk_bf16_f32 v9, v10, v11
	v_cvt_pk_bf16_f32 v10, v12, v13
	v_cvt_pk_bf16_f32 v11, v14, v15
	global_store_dwordx4 v[40:41], v[8:11], off offset:16
	s_andn2_b64 exec, exec, s[18:19]
	s_cbranch_execz .LBB0_1407

.LBB0_2084:
	s_waitcnt vmcnt(34)
	v_pk_fma_f32 v[16:17], v[16:17], v[206:207], v[0:1]
	v_add_u32_e32 v0, 15, v144
	v_mad_u64_u32 v[44:45], s[12:13], v0, s27, v[108:109]
	v_pk_fma_f32 v[12:13], v[28:29], v[198:199], v[12:13]
	v_pk_fma_f32 v[14:15], v[30:31], v[216:217], v[14:15]
	s_waitcnt vmcnt(32)
	v_pk_fma_f32 v[24:25], v[24:25], v[214:215], v[8:9]
	v_pk_fma_f32 v[26:27], v[26:27], v[212:213], v[10:11]
	v_pk_fma_f32 v[8:9], v[20:21], v[210:211], v[4:5]
	v_pk_fma_f32 v[10:11], v[22:23], v[208:209], v[6:7]
	v_pk_fma_f32 v[18:19], v[18:19], v[204:205], v[2:3]
	v_add_co_u32_e32 v46, vcc, s57, v44
	global_store_dwordx4 v[160:161], v[12:15], off
	global_store_dwordx4 v[160:161], v[24:27], off offset:16
	global_store_dwordx4 v[160:161], v[8:11], off offset:32
	global_store_dwordx4 v[160:161], v[16:19], off offset:48
	v_addc_co_u32_e32 v47, vcc, 0, v45, vcc
	global_load_dwordx4 v[0:3], v[106:107], off offset:16
	global_load_dwordx4 v[4:7], v[106:107], off
	global_load_dwordx4 v[20:23], v[46:47], off
	v_lshl_add_u64 v[28:29], v[44:45], 0, s[20:21]
	global_load_dwordx4 v[28:31], v[28:29], off offset:16
	s_nop 0
	global_load_dwordx4 v[32:35], v[44:45], off offset:16
	global_load_dwordx4 v[36:39], v[44:45], off
	v_mov_b32_e32 v60, v0
	v_mov_b32_e32 v61, v1
	global_load_dwordx4 v[200:203], v[106:107], off offset:32
	global_load_dwordx4 v[194:197], v[46:47], off offset:32
	global_load_dwordx4 v[190:193], v[106:107], off offset:48
	v_lshl_add_u64 v[60:61], v[44:45], 0, s[22:23]
	global_load_dwordx4 v[186:189], v[60:61], off offset:16
	global_load_dwordx4 v[182:185], v[44:45], off offset:32
	global_load_dwordx4 v[178:181], v[44:45], off offset:48
	v_pk_mul_f32 v[40:41], v[12:13], v[12:13]
	v_pk_mul_f32 v[42:43], v[14:15], v[14:15]
	v_add_f32_e32 v40, v40, v41
	v_add_f32_e32 v40, v40, v42
	v_pk_mul_f32 v[48:49], v[24:25], v[24:25]
	v_add_f32_e32 v40, v43, v40
	v_add_f32_e32 v40, v48, v40
	v_pk_mul_f32 v[50:51], v[26:27], v[26:27]
	v_add_f32_e32 v40, v49, v40
	v_add_f32_e32 v40, v50, v40
	v_pk_mul_f32 v[52:53], v[8:9], v[8:9]
	v_add_f32_e32 v40, v51, v40
	v_add_f32_e32 v40, v52, v40
	v_pk_mul_f32 v[54:55], v[10:11], v[10:11]
	v_add_f32_e32 v40, v53, v40
	v_add_f32_e32 v40, v54, v40
	v_pk_mul_f32 v[56:57], v[16:17], v[16:17]
	v_add_f32_e32 v40, v55, v40
	v_add_f32_e32 v40, v56, v40
	v_pk_mul_f32 v[58:59], v[18:19], v[18:19]
	v_add_f32_e32 v40, v57, v40
	v_add_f32_e32 v40, v58, v40
	v_add_f32_e32 v40, v59, v40
	v_accvgpr_read_b32 v41, a71
	ds_bpermute_b32 v41, v41, v40
	v_mov_b32_e32 v42, 0x358637bd
	v_mov_b32_e32 v102, v118
	v_mov_b32_e32 v116, v120
	s_waitcnt vmcnt(19)
	v_accvgpr_read_b32 v142, a68
	s_waitcnt lgkmcnt(0)
	v_add_f32_e32 v40, v40, v41
	v_accvgpr_read_b32 v41, a74
	ds_bpermute_b32 v41, v41, v40
	s_waitcnt vmcnt(18)
	v_accvgpr_read_b32 v143, a69
	s_waitcnt lgkmcnt(0)
	v_add_f32_e32 v40, v40, v41
	v_accvgpr_read_b32 v41, a75
	ds_bpermute_b32 v41, v41, v40
	s_waitcnt lgkmcnt(0)
	v_add_f32_e32 v40, v40, v41
	ds_bpermute_b32 v41, v135, v40
	s_waitcnt lgkmcnt(0)
	v_add_f32_e32 v40, v40, v41
	ds_bpermute_b32 v41, v129, v40
	s_waitcnt lgkmcnt(0)
	v_add_f32_e32 v40, v40, v41
	ds_bpermute_b32 v41, v131, v40
	s_waitcnt lgkmcnt(0)
	v_add_f32_e32 v40, v40, v41
	v_fmamk_f32 v40, v40, 0x3a800000, v42
	v_mul_f32_e32 v41, 0x4b800000, v40
	v_cmp_gt_f32_e32 vcc, s56, v40
	s_nop 1
	v_cndmask_b32_e32 v40, v40, v41, vcc
	v_rsq_f32_e32 v42, v40
	v_lshl_add_u64 v[40:41], v[122:123], 1, v[104:105]
	v_mul_f32_e32 v43, 0x45800000, v42
	v_cndmask_b32_e32 v42, v42, v43, vcc
	v_pk_mul_f32 v[12:13], v[12:13], v[42:43] op_sel_hi:[1,0]
	v_pk_mul_f32 v[14:15], v[14:15], v[42:43] op_sel_hi:[1,0]
	v_pk_mul_f32 v[24:25], v[24:25], v[42:43] op_sel_hi:[1,0]
	v_pk_mul_f32 v[26:27], v[26:27], v[42:43] op_sel_hi:[1,0]
	s_waitcnt vmcnt(10)
	v_pk_mul_f32 v[4:5], v[4:5], v[12:13]
	v_pk_mul_f32 v[6:7], v[6:7], v[14:15]
	v_pk_mul_f32 v[0:1], v[24:25], v[0:1]
	v_pk_mul_f32 v[2:3], v[26:27], v[2:3]
	s_waitcnt vmcnt(9)
	v_pk_add_f32 v[12:13], v[20:21], 1.0 op_sel_hi:[1,0]
	v_pk_add_f32 v[14:15], v[22:23], 1.0 op_sel_hi:[1,0]
	s_waitcnt vmcnt(8)
	v_pk_add_f32 v[20:21], v[28:29], 1.0 op_sel_hi:[1,0]
	v_pk_add_f32 v[22:23], v[30:31], 1.0 op_sel_hi:[1,0]
	s_waitcnt vmcnt(6)
	v_pk_fma_f32 v[4:5], v[12:13], v[4:5], v[36:37]
	v_pk_fma_f32 v[6:7], v[6:7], v[14:15], v[38:39]
	v_pk_fma_f32 v[12:13], v[0:1], v[20:21], v[32:33]
	v_pk_fma_f32 v[14:15], v[2:3], v[22:23], v[34:35]
	v_cvt_pk_bf16_f32 v0, v4, v5
	v_cvt_pk_bf16_f32 v1, v6, v7
	v_cvt_pk_bf16_f32 v2, v12, v13
	v_cvt_pk_bf16_f32 v3, v14, v15
	global_store_dwordx4 v[40:41], v[0:3], off
	s_waitcnt vmcnt(6)
	s_nop 1
	v_mov_b64_e32 v[12:13], v[200:201]
	v_mov_b64_e32 v[14:15], v[202:203]
	s_waitcnt vmcnt(5)
	s_nop 1
	v_mov_b64_e32 v[20:21], v[194:195]
	v_mov_b64_e32 v[22:23], v[196:197]
	s_waitcnt vmcnt(4)
	s_nop 1
	v_mov_b64_e32 v[24:25], v[190:191]
	v_mov_b64_e32 v[26:27], v[192:193]
	v_lshl_add_u64 v[0:1], v[44:45], 0, s[22:23]
	s_waitcnt vmcnt(3)
	s_nop 1
	v_mov_b64_e32 v[28:29], v[186:187]
	v_mov_b64_e32 v[30:31], v[188:189]
	s_waitcnt vmcnt(2)
	s_nop 1
	v_mov_b64_e32 v[32:33], v[182:183]
	v_mov_b64_e32 v[34:35], v[184:185]
	s_waitcnt vmcnt(1)
	s_nop 1
	v_mov_b64_e32 v[36:37], v[178:179]
	v_mov_b64_e32 v[38:39], v[180:181]
	v_pk_mul_f32 v[8:9], v[8:9], v[42:43] op_sel_hi:[1,0]
	v_pk_mul_f32 v[10:11], v[10:11], v[42:43] op_sel_hi:[1,0]
	v_pk_mul_f32 v[16:17], v[16:17], v[42:43] op_sel_hi:[1,0]
	v_pk_mul_f32 v[18:19], v[18:19], v[42:43] op_sel_hi:[1,0]
	v_cmp_lt_i32_e32 vcc, s31, v128
	v_accvgpr_read_b32 v4, a32
	v_accvgpr_read_b32 v0, a28
	v_accvgpr_read_b32 v5, a33
	v_accvgpr_read_b32 v6, a34
	v_accvgpr_read_b32 v7, a35
	v_accvgpr_read_b32 v1, a29
	v_accvgpr_read_b32 v2, a30
	v_accvgpr_read_b32 v3, a31
	s_or_b64 s[18:19], vcc, s[18:19]
	v_pk_mul_f32 v[8:9], v[8:9], v[12:13]
	v_pk_add_f32 v[12:13], v[20:21], 1.0 op_sel_hi:[1,0]
	v_pk_mul_f32 v[10:11], v[10:11], v[14:15]
	v_pk_add_f32 v[14:15], v[22:23], 1.0 op_sel_hi:[1,0]
	v_pk_mul_f32 v[16:17], v[16:17], v[24:25]
	v_pk_add_f32 v[20:21], v[28:29], 1.0 op_sel_hi:[1,0]
	v_pk_mul_f32 v[18:19], v[18:19], v[26:27]
	v_pk_add_f32 v[22:23], v[30:31], 1.0 op_sel_hi:[1,0]
	v_pk_fma_f32 v[8:9], v[8:9], v[12:13], v[32:33]
	v_pk_fma_f32 v[10:11], v[10:11], v[14:15], v[34:35]
	v_pk_fma_f32 v[12:13], v[16:17], v[20:21], v[36:37]
	v_pk_fma_f32 v[14:15], v[18:19], v[22:23], v[38:39]
	v_cvt_pk_bf16_f32 v8, v8, v9
	v_cvt_pk_bf16_f32 v9, v10, v11
	v_cvt_pk_bf16_f32 v10, v12, v13
	v_cvt_pk_bf16_f32 v11, v14, v15
	global_store_dwordx4 v[40:41], v[8:11], off offset:16
	s_andn2_b64 exec, exec, s[18:19]
	s_cbranch_execz .LBB0_2106
